# hand-written P7 residual epilogue (all params + 3 row-groups of xold in flight, full-line xnew/xs stores) on top of v41; dtype comment
# baseline (speedup 1.0000x reference)
; __device__ __forceinline__ void store_lines(PG8_LAS unsigned char* stg, const u32x4 P0, const u32x4 P1, int fr, int fq, bf16_t* seg0, int pitch) {
;     const int ln = fq * 16 + fr;
; #pragma unroll
;     for (int h = 0; h < 2; ++h) {
;         if ((fr >> 3) == h) { *(PG8_LAS u32x4*)(stg + (fr & 7) * 128 + fq * 16) = P0; *(PG8_LAS u32x4*)(stg + (fr & 7) * 128 + 64 + fq * 16) = P1; }
;     __device__ __forceinline__ void operator()(const f32x4 (&acc)[2][2][4][2], const Unit& u, int wr, int wc, int fr, int fq) const {
;         asm volatile("" : "+v"(fr), "+v"(fq));
;         const int b = u.pm >> 5, col0 = u.pn * BM + wc * 64 + fq * 8;
;         PG8_LAS unsigned char* st = stg + (wr * 4 + wc) * 1024;
;         f32x4 gv[2][2], cs[2][2];
; #pragma unroll
;         for (int bj = 0; bj < 2; ++bj)
; #pragma unroll
;             for (int n = 0; n < 2; ++n) { const int c = col0 + bj * 32 + 4 * n; gv[bj][n] = *(const f32x4*)(gate + (size_t)b * NMODC + c) * (HALFG ? 0.5f : 1.0f);
;                 cs[bj][n] = (f32x4){0.f, 0.f, 0.f, 0.f}; if (XS) cs[bj][n] = *(const f32x4*)(gcol + c) * (*(const f32x4*)(scm + (size_t)b * NMODC + c) + 1.0f); }
;         u32x4 c16[2], n16[2]; f32x4 c32[2][2], n32[2][2];
;     ...
;         RES_LOAD(c16, c32, 0);
; #pragma unroll
;         for (int r = 0; r < 8; ++r) { const int ai = r >> 2, m = r & 3; const int row = EPI_ROW; float sq = 0.f;
;             if (r < 7) RES_LOAD(n16, n32, r + 1);
;             u32x4 pn_[2], ps_[2];
; #pragma unroll
;             for (int bj = 0; bj < 2; ++bj) {
;                 f32x4 o0, o1;
;                 if (XOLD16) unpack8(c16[bj], o0, o1); else { o0 = c32[bj][0]; o1 = c32[bj][1]; }
;                 const f32x4 v0 = o0 + gv[bj][0] * acc[ai][bj][m][0], v1 = o1 + gv[bj][1] * acc[ai][bj][m][1];
;                 pn_[bj] = pack8(v0, v1);
;                 sq += ((v0[0] * v0[0] + v0[1] * v0[1]) + (v0[2] * v0[2] + v0[3] * v0[3])) + ((v1[0] * v1[0] + v1[1] * v1[1]) + (v1[2] * v1[2] + v1[3] * v1[3]));
;                 if (XS) ps_[bj] = pack8(v0 * cs[bj][0], v1 * cs[bj][1]); }
;             { const size_t seg = (size_t)(row - fr) * DM + u.pn * BM + wc * 64;
;               store_lines(st, pn_[0], pn_[1], fr, fq, xnew + seg, DM);
;               if (XS) store_lines(st, ps_[0], ps_[1], fr, fq, xs + seg, DM); }
;             sq += __shfl_xor(sq, 16); sq += __shfl_xor(sq, 32);
.LBB0_841:
	s_mov_b32 s98, s0
	s_lshl_b32 s1, s14, 8
	s_or_b32 s1, s1, s24
	s_lshl_b32 s4, s98, 8
	s_add_i32 s4, s4, s62
	s_ashr_i32 s5, s98, 5
	s_mul_i32 s5, s5, 0x9000
	s_lshl_b32 s6, s1, 2
	s_add_u32 s5, s5, s6
	s_add_u32 s36, s55, s5
	s_addc_u32 s37, s56, 0
	s_add_u32 s38, s59, s5
	s_addc_u32 s39, s60, 0
	s_add_u32 s40, s10, s6
	s_addc_u32 s41, s11, 0
	v_lshlrev_b32_e32 v150, 5, v212
	global_load_dwordx4 v[184:187], v150, s[36:37]
	global_load_dwordx4 v[180:183], v150, s[36:37] offset:16
	global_load_dwordx4 v[176:179], v150, s[36:37] offset:128
	global_load_dwordx4 v[172:175], v150, s[36:37] offset:144
	global_load_dwordx4 v[200:203], v150, s[38:39]
	global_load_dwordx4 v[196:199], v150, s[38:39] offset:16
	global_load_dwordx4 v[192:195], v150, s[38:39] offset:128
	global_load_dwordx4 v[188:191], v150, s[38:39] offset:144
	global_load_dwordx4 v[236:239], v150, s[40:41]
	global_load_dwordx4 v[232:235], v150, s[40:41] offset:16
	global_load_dwordx4 v[228:231], v150, s[40:41] offset:128
	global_load_dwordx4 v[224:227], v150, s[40:41] offset:144
	s_lshl_b32 s5, s4, 11
	s_lshl_b32 s6, s1, 1
	s_add_u32 s5, s5, s6
	s_add_u32 s36, s12, s5
	s_addc_u32 s37, s13, 0
	s_add_u32 s38, s100, s5
	s_addc_u32 s39, s101, 0
	s_add_u32 s40, s57, s5
	s_addc_u32 s41, s58, 0
	v_lshlrev_b32_e32 v151, 11, v1
	v_lshl_add_u32 v151, v212, 4, v151
	global_load_dwordx4 v[240:243], v151, s[36:37]
	global_load_dwordx4 v[244:247], v151, s[36:37] offset:64
	s_add_u32 s36, s36, 0x8000
	s_addc_u32 s37, s37, 0
	global_load_dwordx4 v[248:251], v151, s[36:37]
	global_load_dwordx4 v[204:207], v151, s[36:37] offset:64
	s_add_u32 s36, s36, 0x8000
	s_addc_u32 s37, s37, 0
	global_load_dwordx4 v[50:53], v151, s[36:37]
	global_load_dwordx4 v[54:57], v151, s[36:37] offset:64
	s_add_u32 s36, s36, 0x8000
	s_addc_u32 s37, s37, 0
	v_lshlrev_b32_e32 v152, 6, v1
	s_lshl_b32 s5, s62, 7
	s_lshl_b32 s6, s61, 11
	s_add_i32 s5, s5, s6
	s_add_i32 s5, s5, 0x20000
	v_lshlrev_b32_e32 v153, 7, v1
	v_lshl_add_u32 v153, v212, 4, v153
	v_add_u32_e32 v153, s5, v153
	v_lshl_add_u32 v162, v217, 4, s5
	v_lshrrev_b32_e32 v255, 3, v217
	v_lshlrev_b32_e32 v255, 11, v255
	v_and_b32_e32 v208, 7, v217
	v_lshl_add_u32 v255, v208, 4, v255
	s_waitcnt vmcnt(6)
	v_pk_add_f32 v[188:189], v[188:189], 1.0 op_sel_hi:[1,0]
	v_pk_add_f32 v[190:191], v[190:191], 1.0 op_sel_hi:[1,0]
	v_pk_add_f32 v[192:193], v[192:193], 1.0 op_sel_hi:[1,0]
	v_pk_add_f32 v[194:195], v[194:195], 1.0 op_sel_hi:[1,0]
	v_pk_add_f32 v[196:197], v[196:197], 1.0 op_sel_hi:[1,0]
	v_pk_add_f32 v[198:199], v[198:199], 1.0 op_sel_hi:[1,0]
	v_pk_add_f32 v[200:201], v[200:201], 1.0 op_sel_hi:[1,0]
	v_pk_add_f32 v[202:203], v[202:203], 1.0 op_sel_hi:[1,0]
	v_pk_mul_f32 v[188:189], v[224:225], v[188:189]
	v_pk_mul_f32 v[190:191], v[226:227], v[190:191]
	v_pk_mul_f32 v[192:193], v[228:229], v[192:193]
	v_pk_mul_f32 v[194:195], v[230:231], v[194:195]
	v_pk_mul_f32 v[196:197], v[232:233], v[196:197]
	v_pk_mul_f32 v[198:199], v[234:235], v[198:199]
	v_pk_mul_f32 v[200:201], v[236:237], v[200:201]
	v_pk_mul_f32 v[202:203], v[238:239], v[202:203]
	s_waitcnt vmcnt(4)
	v_lshlrev_b32_e32 v236, 16, v240
	v_and_b32_e32 v237, 0xffff0000, v240
	v_lshlrev_b32_e32 v238, 16, v241
	v_and_b32_e32 v239, 0xffff0000, v241
	v_lshlrev_b32_e32 v232, 16, v242
	v_and_b32_e32 v233, 0xffff0000, v242
	v_lshlrev_b32_e32 v234, 16, v243
	v_and_b32_e32 v235, 0xffff0000, v243
	v_lshlrev_b32_e32 v228, 16, v244
	v_and_b32_e32 v229, 0xffff0000, v244
	v_lshlrev_b32_e32 v230, 16, v245
	v_and_b32_e32 v231, 0xffff0000, v245
	v_lshlrev_b32_e32 v224, 16, v246
	v_and_b32_e32 v225, 0xffff0000, v246
	v_lshlrev_b32_e32 v226, 16, v247
	v_and_b32_e32 v227, 0xffff0000, v247
	global_load_dwordx4 v[240:243], v151, s[36:37]
	global_load_dwordx4 v[244:247], v151, s[36:37] offset:64
	s_add_u32 s36, s36, 0x28000
	s_addc_u32 s37, s37, 0
	v_pk_fma_f32 v[142:143], v[142:143], v[184:185], v[236:237]
	v_pk_fma_f32 v[144:145], v[144:145], v[186:187], v[238:239]
	v_pk_fma_f32 v[138:139], v[138:139], v[180:181], v[232:233]
	v_pk_fma_f32 v[140:141], v[140:141], v[182:183], v[234:235]
	v_pk_fma_f32 v[134:135], v[134:135], v[176:177], v[228:229]
	v_pk_fma_f32 v[136:137], v[136:137], v[178:179], v[230:231]
	v_pk_fma_f32 v[130:131], v[130:131], v[172:173], v[224:225]
	v_pk_fma_f32 v[132:133], v[132:133], v[174:175], v[226:227]
	v_mul_f32_e32 v224, v143, v143
	v_mul_f32_e32 v225, v145, v145
	v_fmac_f32_e32 v224, v142, v142
	v_fmac_f32_e32 v225, v144, v144
	v_add_f32_e32 v224, v224, v225
	v_mul_f32_e32 v225, v139, v139
	v_mul_f32_e32 v226, v141, v141
	v_fmac_f32_e32 v225, v138, v138
	v_fmac_f32_e32 v226, v140, v140
	v_add_f32_e32 v225, v225, v226
	v_add_f32_e32 v224, v224, v225
	v_mul_f32_e32 v225, v135, v135
	v_mul_f32_e32 v226, v137, v137
	v_fmac_f32_e32 v225, v134, v134
	v_fmac_f32_e32 v226, v136, v136
	v_add_f32_e32 v225, v225, v226
	v_mul_f32_e32 v226, v131, v131
	v_mul_f32_e32 v227, v133, v133
	v_fmac_f32_e32 v226, v130, v130
	v_fmac_f32_e32 v227, v132, v132
	v_add_f32_e32 v226, v226, v227
	v_add_f32_e32 v225, v225, v226
	v_add_f32_e32 v218, v224, v225
	v_cvt_pk_bf16_f32 v66, v142, v143
	v_cvt_pk_bf16_f32 v67, v144, v145
	v_cvt_pk_bf16_f32 v68, v138, v139
	v_cvt_pk_bf16_f32 v69, v140, v141
	v_cvt_pk_bf16_f32 v70, v134, v135
	v_cvt_pk_bf16_f32 v71, v136, v137
	v_cvt_pk_bf16_f32 v72, v130, v131
	v_cvt_pk_bf16_f32 v73, v132, v133
	ds_write_b128 v153, v[66:69]
	ds_write_b128 v153, v[70:73] offset:64
	ds_read_b128 v[208:211], v162
	ds_read_b128 v[146:149], v162 offset:1024
	s_add_u32 s4, s38, 0x4000
	s_addc_u32 s5, s39, 0
	s_waitcnt lgkmcnt(1)
	global_store_dwordx4 v255, v[208:211], s[38:39]
	s_waitcnt lgkmcnt(0)
; #define PG8_LAS __attribute__((address_space(3)))
; __device__ __forceinline__ u32x4 pack8(const f32x4 a, const f32x4 b) { u32x4 w; w.x = cvt_pk_bf16(a[0], a[1]); w.y = cvt_pk_bf16(a[2], a[3]); w.z = cvt_pk_bf16(b[0], b[1]); w.w = cvt_pk_bf16(b[2], b[3]); return w; }
; __device__ __forceinline__ void store_lines(PG8_LAS unsigned char* stg, const u32x4 P0, const u32x4 P1, int fr, int fq, bf16_t* seg0, int pitch) {
;     const int ln = fq * 16 + fr;
; #pragma unroll
;     for (int h = 0; h < 2; ++h) {
;         if ((fr >> 3) == h) { *(PG8_LAS u32x4*)(stg + (fr & 7) * 128 + fq * 16) = P0; *(PG8_LAS u32x4*)(stg + (fr & 7) * 128 + 64 + fq * 16) = P1; }
;         __builtin_amdgcn_wave_barrier(); asm volatile("" ::: "memory");
;         const u32x4 v = *(const PG8_LAS u32x4*)(stg + ln * 16);
;         __builtin_amdgcn_wave_barrier(); asm volatile("" ::: "memory");
;         *(u32x4*)(seg0 + (size_t)(8 * h + (ln >> 3)) * pitch + (ln & 7) * 8) = v; }
;     __device__ __forceinline__ void operator()(const f32x4 (&acc)[2][2][4][2], const Unit& u, int wr, int wc, int fr, int fq) const {
;     ...
;         for (int r = 0; r < 8; ++r) { const int ai = r >> 2, m = r & 3; const int row = EPI_ROW; float sq = 0.f;
;             if (r < 7) RES_LOAD(n16, n32, r + 1);
;             u32x4 pn_[2], ps_[2];
; #pragma unroll
;             for (int bj = 0; bj < 2; ++bj) {
;                 f32x4 o0, o1;
;                 if (XOLD16) unpack8(c16[bj], o0, o1); else { o0 = c32[bj][0]; o1 = c32[bj][1]; }
;                 const f32x4 v0 = o0 + gv[bj][0] * acc[ai][bj][m][0], v1 = o1 + gv[bj][1] * acc[ai][bj][m][1];
;                 pn_[bj] = pack8(v0, v1);
;                 sq += ((v0[0] * v0[0] + v0[1] * v0[1]) + (v0[2] * v0[2] + v0[3] * v0[3])) + ((v1[0] * v1[0] + v1[1] * v1[1]) + (v1[2] * v1[2] + v1[3] * v1[3]));
;                 if (XS) ps_[bj] = pack8(v0 * cs[bj][0], v1 * cs[bj][1]); }
;             { const size_t seg = (size_t)(row - fr) * DM + u.pn * BM + wc * 64;
;               store_lines(st, pn_[0], pn_[1], fr, fq, xnew + seg, DM);
;               if (XS) store_lines(st, ps_[0], ps_[1], fr, fq, xs + seg, DM); }
	global_store_dwordx4 v255, v[146:149], s[4:5]
	v_pk_mul_f32 v[236:237], v[200:201], v[142:143]
	v_pk_mul_f32 v[238:239], v[202:203], v[144:145]
	v_pk_mul_f32 v[232:233], v[196:197], v[138:139]
	v_pk_mul_f32 v[234:235], v[198:199], v[140:141]
	v_pk_mul_f32 v[228:229], v[192:193], v[134:135]
	v_pk_mul_f32 v[230:231], v[194:195], v[136:137]
	v_pk_mul_f32 v[224:225], v[188:189], v[130:131]
	v_pk_mul_f32 v[226:227], v[190:191], v[132:133]
	v_cvt_pk_bf16_f32 v66, v236, v237
	v_cvt_pk_bf16_f32 v67, v238, v239
	v_cvt_pk_bf16_f32 v68, v232, v233
	v_cvt_pk_bf16_f32 v69, v234, v235
	v_cvt_pk_bf16_f32 v70, v228, v229
	v_cvt_pk_bf16_f32 v71, v230, v231
	v_cvt_pk_bf16_f32 v72, v224, v225
	v_cvt_pk_bf16_f32 v73, v226, v227
	ds_write_b128 v153, v[66:69]
	ds_write_b128 v153, v[70:73] offset:64
	ds_read_b128 v[208:211], v162
	ds_read_b128 v[146:149], v162 offset:1024
	s_add_u32 s4, s40, 0x4000
	s_addc_u32 s5, s41, 0
	s_waitcnt lgkmcnt(1)
	global_store_dwordx4 v255, v[208:211], s[40:41]
	s_waitcnt lgkmcnt(0)
	global_store_dwordx4 v255, v[146:149], s[4:5]
	s_add_u32 s38, s38, 0x8000
	s_addc_u32 s39, s39, 0
	s_add_u32 s40, s40, 0x8000
	s_addc_u32 s41, s41, 0
	s_waitcnt vmcnt(8)
	v_lshlrev_b32_e32 v236, 16, v248
	v_and_b32_e32 v237, 0xffff0000, v248
	v_lshlrev_b32_e32 v238, 16, v249
	v_and_b32_e32 v239, 0xffff0000, v249
	v_lshlrev_b32_e32 v232, 16, v250
	v_and_b32_e32 v233, 0xffff0000, v250
	v_lshlrev_b32_e32 v234, 16, v251
	v_and_b32_e32 v235, 0xffff0000, v251
	v_lshlrev_b32_e32 v228, 16, v204
	v_and_b32_e32 v229, 0xffff0000, v204
	v_lshlrev_b32_e32 v230, 16, v205
	v_and_b32_e32 v231, 0xffff0000, v205
	v_lshlrev_b32_e32 v224, 16, v206
	v_and_b32_e32 v225, 0xffff0000, v206
	v_lshlrev_b32_e32 v226, 16, v207
	v_and_b32_e32 v227, 0xffff0000, v207
	global_load_dwordx4 v[248:251], v151, s[36:37]
	global_load_dwordx4 v[204:207], v151, s[36:37] offset:64
	s_add_u32 s36, s36, 0x8000
	s_addc_u32 s37, s37, 0
	v_pk_fma_f32 v[126:127], v[126:127], v[184:185], v[236:237]
	v_pk_fma_f32 v[128:129], v[128:129], v[186:187], v[238:239]
	v_pk_fma_f32 v[122:123], v[122:123], v[180:181], v[232:233]
	v_pk_fma_f32 v[124:125], v[124:125], v[182:183], v[234:235]
	v_pk_fma_f32 v[118:119], v[118:119], v[176:177], v[228:229]
	v_pk_fma_f32 v[120:121], v[120:121], v[178:179], v[230:231]
	v_pk_fma_f32 v[114:115], v[114:115], v[172:173], v[224:225]
	v_pk_fma_f32 v[116:117], v[116:117], v[174:175], v[226:227]
	v_mul_f32_e32 v224, v127, v127
	v_mul_f32_e32 v225, v129, v129
	v_fmac_f32_e32 v224, v126, v126
	v_fmac_f32_e32 v225, v128, v128
	v_add_f32_e32 v224, v224, v225
	v_mul_f32_e32 v225, v123, v123
	v_mul_f32_e32 v226, v125, v125
	v_fmac_f32_e32 v225, v122, v122
	v_fmac_f32_e32 v226, v124, v124
	v_add_f32_e32 v225, v225, v226
	v_add_f32_e32 v224, v224, v225
	v_mul_f32_e32 v225, v119, v119
	v_mul_f32_e32 v226, v121, v121
	v_fmac_f32_e32 v225, v118, v118
	v_fmac_f32_e32 v226, v120, v120
	v_add_f32_e32 v225, v225, v226
	v_mul_f32_e32 v226, v115, v115
	v_mul_f32_e32 v227, v117, v117
	v_fmac_f32_e32 v226, v114, v114
	v_fmac_f32_e32 v227, v116, v116
	v_add_f32_e32 v226, v226, v227
	v_add_f32_e32 v225, v225, v226
	v_add_f32_e32 v219, v224, v225
	v_cvt_pk_bf16_f32 v66, v126, v127
	v_cvt_pk_bf16_f32 v67, v128, v129
	v_cvt_pk_bf16_f32 v68, v122, v123
	v_cvt_pk_bf16_f32 v69, v124, v125
	v_cvt_pk_bf16_f32 v70, v118, v119
	v_cvt_pk_bf16_f32 v71, v120, v121
	v_cvt_pk_bf16_f32 v72, v114, v115
	v_cvt_pk_bf16_f32 v73, v116, v117
	ds_write_b128 v153, v[66:69]
	ds_write_b128 v153, v[70:73] offset:64
	ds_read_b128 v[208:211], v162
	ds_read_b128 v[146:149], v162 offset:1024
	s_add_u32 s4, s38, 0x4000
	s_addc_u32 s5, s39, 0
	s_waitcnt lgkmcnt(1)
	global_store_dwordx4 v255, v[208:211], s[38:39]
	s_waitcnt lgkmcnt(0)
	global_store_dwordx4 v255, v[146:149], s[4:5]
	v_pk_mul_f32 v[236:237], v[200:201], v[126:127]
	v_pk_mul_f32 v[238:239], v[202:203], v[128:129]
	v_pk_mul_f32 v[232:233], v[196:197], v[122:123]
	v_pk_mul_f32 v[234:235], v[198:199], v[124:125]
	v_pk_mul_f32 v[228:229], v[192:193], v[118:119]
	v_pk_mul_f32 v[230:231], v[194:195], v[120:121]
	v_pk_mul_f32 v[224:225], v[188:189], v[114:115]
	v_pk_mul_f32 v[226:227], v[190:191], v[116:117]
	v_cvt_pk_bf16_f32 v66, v236, v237
	v_cvt_pk_bf16_f32 v67, v238, v239
	v_cvt_pk_bf16_f32 v68, v232, v233
	v_cvt_pk_bf16_f32 v69, v234, v235
	v_cvt_pk_bf16_f32 v70, v228, v229
	v_cvt_pk_bf16_f32 v71, v230, v231
	v_cvt_pk_bf16_f32 v72, v224, v225
	v_cvt_pk_bf16_f32 v73, v226, v227
	ds_write_b128 v153, v[66:69]
	ds_write_b128 v153, v[70:73] offset:64
	ds_read_b128 v[208:211], v162
	ds_read_b128 v[146:149], v162 offset:1024
	s_add_u32 s4, s40, 0x4000
	s_addc_u32 s5, s41, 0
	s_waitcnt lgkmcnt(1)
	global_store_dwordx4 v255, v[208:211], s[40:41]
	s_waitcnt lgkmcnt(0)
	global_store_dwordx4 v255, v[146:149], s[4:5]
	s_add_u32 s38, s38, 0x8000
	s_addc_u32 s39, s39, 0
	s_add_u32 s40, s40, 0x8000
	s_addc_u32 s41, s41, 0
	s_waitcnt vmcnt(12)
; #define PG8_LAS __attribute__((address_space(3)))
; __device__ __forceinline__ u32x4 pack8(const f32x4 a, const f32x4 b) { u32x4 w; w.x = cvt_pk_bf16(a[0], a[1]); w.y = cvt_pk_bf16(a[2], a[3]); w.z = cvt_pk_bf16(b[0], b[1]); w.w = cvt_pk_bf16(b[2], b[3]); return w; }
; __device__ __forceinline__ void store_lines(PG8_LAS unsigned char* stg, const u32x4 P0, const u32x4 P1, int fr, int fq, bf16_t* seg0, int pitch) {
;     const int ln = fq * 16 + fr;
; #pragma unroll
;     for (int h = 0; h < 2; ++h) {
;         if ((fr >> 3) == h) { *(PG8_LAS u32x4*)(stg + (fr & 7) * 128 + fq * 16) = P0; *(PG8_LAS u32x4*)(stg + (fr & 7) * 128 + 64 + fq * 16) = P1; }
;         __builtin_amdgcn_wave_barrier(); asm volatile("" ::: "memory");
;         const u32x4 v = *(const PG8_LAS u32x4*)(stg + ln * 16);
;         __builtin_amdgcn_wave_barrier(); asm volatile("" ::: "memory");
;         *(u32x4*)(seg0 + (size_t)(8 * h + (ln >> 3)) * pitch + (ln & 7) * 8) = v; }
;     __device__ __forceinline__ void operator()(const f32x4 (&acc)[2][2][4][2], const Unit& u, int wr, int wc, int fr, int fq) const {
;     ...
;         for (int r = 0; r < 8; ++r) { const int ai = r >> 2, m = r & 3; const int row = EPI_ROW; float sq = 0.f;
;             if (r < 7) RES_LOAD(n16, n32, r + 1);
;             u32x4 pn_[2], ps_[2];
; #pragma unroll
;             for (int bj = 0; bj < 2; ++bj) {
;                 f32x4 o0, o1;
;                 if (XOLD16) unpack8(c16[bj], o0, o1); else { o0 = c32[bj][0]; o1 = c32[bj][1]; }
;                 const f32x4 v0 = o0 + gv[bj][0] * acc[ai][bj][m][0], v1 = o1 + gv[bj][1] * acc[ai][bj][m][1];
;                 pn_[bj] = pack8(v0, v1);
;                 sq += ((v0[0] * v0[0] + v0[1] * v0[1]) + (v0[2] * v0[2] + v0[3] * v0[3])) + ((v1[0] * v1[0] + v1[1] * v1[1]) + (v1[2] * v1[2] + v1[3] * v1[3]));
;                 if (XS) ps_[bj] = pack8(v0 * cs[bj][0], v1 * cs[bj][1]); }
;             { const size_t seg = (size_t)(row - fr) * DM + u.pn * BM + wc * 64;
;               store_lines(st, pn_[0], pn_[1], fr, fq, xnew + seg, DM);
;               if (XS) store_lines(st, ps_[0], ps_[1], fr, fq, xs + seg, DM); }
	v_lshlrev_b32_e32 v236, 16, v50
	v_and_b32_e32 v237, 0xffff0000, v50
	v_lshlrev_b32_e32 v238, 16, v51
	v_and_b32_e32 v239, 0xffff0000, v51
	v_lshlrev_b32_e32 v232, 16, v52
	v_and_b32_e32 v233, 0xffff0000, v52
	v_lshlrev_b32_e32 v234, 16, v53
	v_and_b32_e32 v235, 0xffff0000, v53
	v_lshlrev_b32_e32 v228, 16, v54
	v_and_b32_e32 v229, 0xffff0000, v54
	v_lshlrev_b32_e32 v230, 16, v55
	v_and_b32_e32 v231, 0xffff0000, v55
	v_lshlrev_b32_e32 v224, 16, v56
	v_and_b32_e32 v225, 0xffff0000, v56
	v_lshlrev_b32_e32 v226, 16, v57
	v_and_b32_e32 v227, 0xffff0000, v57
	global_load_dwordx4 v[50:53], v151, s[36:37]
	global_load_dwordx4 v[54:57], v151, s[36:37] offset:64
	s_add_u32 s36, s36, 0x8000
	s_addc_u32 s37, s37, 0
	v_pk_fma_f32 v[110:111], v[110:111], v[184:185], v[236:237]
	v_pk_fma_f32 v[112:113], v[112:113], v[186:187], v[238:239]
	v_pk_fma_f32 v[106:107], v[106:107], v[180:181], v[232:233]
	v_pk_fma_f32 v[108:109], v[108:109], v[182:183], v[234:235]
	v_pk_fma_f32 v[102:103], v[102:103], v[176:177], v[228:229]
	v_pk_fma_f32 v[104:105], v[104:105], v[178:179], v[230:231]
	v_pk_fma_f32 v[98:99], v[98:99], v[172:173], v[224:225]
	v_pk_fma_f32 v[100:101], v[100:101], v[174:175], v[226:227]
	v_mul_f32_e32 v224, v111, v111
	v_mul_f32_e32 v225, v113, v113
	v_fmac_f32_e32 v224, v110, v110
	v_fmac_f32_e32 v225, v112, v112
	v_add_f32_e32 v224, v224, v225
	v_mul_f32_e32 v225, v107, v107
	v_mul_f32_e32 v226, v109, v109
	v_fmac_f32_e32 v225, v106, v106
	v_fmac_f32_e32 v226, v108, v108
	v_add_f32_e32 v225, v225, v226
	v_add_f32_e32 v224, v224, v225
	v_mul_f32_e32 v225, v103, v103
	v_mul_f32_e32 v226, v105, v105
	v_fmac_f32_e32 v225, v102, v102
	v_fmac_f32_e32 v226, v104, v104
	v_add_f32_e32 v225, v225, v226
	v_mul_f32_e32 v226, v99, v99
	v_mul_f32_e32 v227, v101, v101
	v_fmac_f32_e32 v226, v98, v98
	v_fmac_f32_e32 v227, v100, v100
	v_add_f32_e32 v226, v226, v227
	v_add_f32_e32 v225, v225, v226
	v_add_f32_e32 v221, v224, v225
	v_cvt_pk_bf16_f32 v66, v110, v111
	v_cvt_pk_bf16_f32 v67, v112, v113
	v_cvt_pk_bf16_f32 v68, v106, v107
	v_cvt_pk_bf16_f32 v69, v108, v109
	v_cvt_pk_bf16_f32 v70, v102, v103
	v_cvt_pk_bf16_f32 v71, v104, v105
	v_cvt_pk_bf16_f32 v72, v98, v99
	v_cvt_pk_bf16_f32 v73, v100, v101
	ds_write_b128 v153, v[66:69]
	ds_write_b128 v153, v[70:73] offset:64
	ds_read_b128 v[208:211], v162
	ds_read_b128 v[146:149], v162 offset:1024
	s_add_u32 s4, s38, 0x4000
	s_addc_u32 s5, s39, 0
	s_waitcnt lgkmcnt(1)
	global_store_dwordx4 v255, v[208:211], s[38:39]
	s_waitcnt lgkmcnt(0)
	global_store_dwordx4 v255, v[146:149], s[4:5]
	v_pk_mul_f32 v[236:237], v[200:201], v[110:111]
	v_pk_mul_f32 v[238:239], v[202:203], v[112:113]
	v_pk_mul_f32 v[232:233], v[196:197], v[106:107]
	v_pk_mul_f32 v[234:235], v[198:199], v[108:109]
	v_pk_mul_f32 v[228:229], v[192:193], v[102:103]
	v_pk_mul_f32 v[230:231], v[194:195], v[104:105]
	v_pk_mul_f32 v[224:225], v[188:189], v[98:99]
	v_pk_mul_f32 v[226:227], v[190:191], v[100:101]
	v_cvt_pk_bf16_f32 v66, v236, v237
	v_cvt_pk_bf16_f32 v67, v238, v239
	v_cvt_pk_bf16_f32 v68, v232, v233
	v_cvt_pk_bf16_f32 v69, v234, v235
	v_cvt_pk_bf16_f32 v70, v228, v229
	v_cvt_pk_bf16_f32 v71, v230, v231
	v_cvt_pk_bf16_f32 v72, v224, v225
	v_cvt_pk_bf16_f32 v73, v226, v227
	ds_write_b128 v153, v[66:69]
	ds_write_b128 v153, v[70:73] offset:64
	ds_read_b128 v[208:211], v162
	ds_read_b128 v[146:149], v162 offset:1024
	s_add_u32 s4, s40, 0x4000
	s_addc_u32 s5, s41, 0
	s_waitcnt lgkmcnt(1)
	global_store_dwordx4 v255, v[208:211], s[40:41]
	s_waitcnt lgkmcnt(0)
	global_store_dwordx4 v255, v[146:149], s[4:5]
	s_add_u32 s38, s38, 0x8000
	s_addc_u32 s39, s39, 0
	s_add_u32 s40, s40, 0x8000
	s_addc_u32 s41, s41, 0
	s_waitcnt vmcnt(16)
	v_lshlrev_b32_e32 v236, 16, v240
	v_and_b32_e32 v237, 0xffff0000, v240
	v_lshlrev_b32_e32 v238, 16, v241
	v_and_b32_e32 v239, 0xffff0000, v241
	v_lshlrev_b32_e32 v232, 16, v242
	v_and_b32_e32 v233, 0xffff0000, v242
	v_lshlrev_b32_e32 v234, 16, v243
	v_and_b32_e32 v235, 0xffff0000, v243
	v_lshlrev_b32_e32 v228, 16, v244
	v_and_b32_e32 v229, 0xffff0000, v244
	v_lshlrev_b32_e32 v230, 16, v245
	v_and_b32_e32 v231, 0xffff0000, v245
	v_lshlrev_b32_e32 v224, 16, v246
	v_and_b32_e32 v225, 0xffff0000, v246
	v_lshlrev_b32_e32 v226, 16, v247
	v_and_b32_e32 v227, 0xffff0000, v247
	global_load_dwordx4 v[240:243], v151, s[36:37]
	global_load_dwordx4 v[244:247], v151, s[36:37] offset:64
	s_add_u32 s36, s36, 0x8000
	s_addc_u32 s37, s37, 0
	v_pk_fma_f32 v[94:95], v[94:95], v[184:185], v[236:237]
	v_pk_fma_f32 v[96:97], v[96:97], v[186:187], v[238:239]
	v_pk_fma_f32 v[90:91], v[90:91], v[180:181], v[232:233]
	v_pk_fma_f32 v[92:93], v[92:93], v[182:183], v[234:235]
	v_pk_fma_f32 v[86:87], v[86:87], v[176:177], v[228:229]
	v_pk_fma_f32 v[88:89], v[88:89], v[178:179], v[230:231]
	v_pk_fma_f32 v[82:83], v[82:83], v[172:173], v[224:225]
	v_pk_fma_f32 v[84:85], v[84:85], v[174:175], v[226:227]
	v_mul_f32_e32 v224, v95, v95
	v_mul_f32_e32 v225, v97, v97
	v_fmac_f32_e32 v224, v94, v94
	v_fmac_f32_e32 v225, v96, v96
	v_add_f32_e32 v224, v224, v225
	v_mul_f32_e32 v225, v91, v91
	v_mul_f32_e32 v226, v93, v93
	v_fmac_f32_e32 v225, v90, v90
	v_fmac_f32_e32 v226, v92, v92
	v_add_f32_e32 v225, v225, v226
	v_add_f32_e32 v224, v224, v225
	v_mul_f32_e32 v225, v87, v87
	v_mul_f32_e32 v226, v89, v89
	v_fmac_f32_e32 v225, v86, v86
	v_fmac_f32_e32 v226, v88, v88
	v_add_f32_e32 v225, v225, v226
	v_mul_f32_e32 v226, v83, v83
	v_mul_f32_e32 v227, v85, v85
	v_fmac_f32_e32 v226, v82, v82
	v_fmac_f32_e32 v227, v84, v84
	v_add_f32_e32 v226, v226, v227
	v_add_f32_e32 v225, v225, v226
	v_add_f32_e32 v222, v224, v225
	v_cvt_pk_bf16_f32 v66, v94, v95
	v_cvt_pk_bf16_f32 v67, v96, v97
	v_cvt_pk_bf16_f32 v68, v90, v91
	v_cvt_pk_bf16_f32 v69, v92, v93
	v_cvt_pk_bf16_f32 v70, v86, v87
	v_cvt_pk_bf16_f32 v71, v88, v89
	v_cvt_pk_bf16_f32 v72, v82, v83
	v_cvt_pk_bf16_f32 v73, v84, v85
	ds_write_b128 v153, v[66:69]
	ds_write_b128 v153, v[70:73] offset:64
	ds_read_b128 v[208:211], v162
	ds_read_b128 v[146:149], v162 offset:1024
	s_add_u32 s4, s38, 0x4000
	s_addc_u32 s5, s39, 0
	s_waitcnt lgkmcnt(1)
; #define PG8_LAS __attribute__((address_space(3)))
; __device__ __forceinline__ u32x4 pack8(const f32x4 a, const f32x4 b) { u32x4 w; w.x = cvt_pk_bf16(a[0], a[1]); w.y = cvt_pk_bf16(a[2], a[3]); w.z = cvt_pk_bf16(b[0], b[1]); w.w = cvt_pk_bf16(b[2], b[3]); return w; }
; __device__ __forceinline__ void store_lines(PG8_LAS unsigned char* stg, const u32x4 P0, const u32x4 P1, int fr, int fq, bf16_t* seg0, int pitch) {
;     const int ln = fq * 16 + fr;
; #pragma unroll
;     for (int h = 0; h < 2; ++h) {
;         if ((fr >> 3) == h) { *(PG8_LAS u32x4*)(stg + (fr & 7) * 128 + fq * 16) = P0; *(PG8_LAS u32x4*)(stg + (fr & 7) * 128 + 64 + fq * 16) = P1; }
;         __builtin_amdgcn_wave_barrier(); asm volatile("" ::: "memory");
;         const u32x4 v = *(const PG8_LAS u32x4*)(stg + ln * 16);
;         __builtin_amdgcn_wave_barrier(); asm volatile("" ::: "memory");
;         *(u32x4*)(seg0 + (size_t)(8 * h + (ln >> 3)) * pitch + (ln & 7) * 8) = v; }
;     __device__ __forceinline__ void operator()(const f32x4 (&acc)[2][2][4][2], const Unit& u, int wr, int wc, int fr, int fq) const {
;     ...
;         for (int r = 0; r < 8; ++r) { const int ai = r >> 2, m = r & 3; const int row = EPI_ROW; float sq = 0.f;
;             if (r < 7) RES_LOAD(n16, n32, r + 1);
;             u32x4 pn_[2], ps_[2];
; #pragma unroll
;             for (int bj = 0; bj < 2; ++bj) {
;                 f32x4 o0, o1;
;                 if (XOLD16) unpack8(c16[bj], o0, o1); else { o0 = c32[bj][0]; o1 = c32[bj][1]; }
;                 const f32x4 v0 = o0 + gv[bj][0] * acc[ai][bj][m][0], v1 = o1 + gv[bj][1] * acc[ai][bj][m][1];
;                 pn_[bj] = pack8(v0, v1);
;                 sq += ((v0[0] * v0[0] + v0[1] * v0[1]) + (v0[2] * v0[2] + v0[3] * v0[3])) + ((v1[0] * v1[0] + v1[1] * v1[1]) + (v1[2] * v1[2] + v1[3] * v1[3]));
;                 if (XS) ps_[bj] = pack8(v0 * cs[bj][0], v1 * cs[bj][1]); }
;             { const size_t seg = (size_t)(row - fr) * DM + u.pn * BM + wc * 64;
;               store_lines(st, pn_[0], pn_[1], fr, fq, xnew + seg, DM);
;               if (XS) store_lines(st, ps_[0], ps_[1], fr, fq, xs + seg, DM); }
	global_store_dwordx4 v255, v[208:211], s[38:39]
	s_waitcnt lgkmcnt(0)
	global_store_dwordx4 v255, v[146:149], s[4:5]
	v_pk_mul_f32 v[236:237], v[200:201], v[94:95]
	v_pk_mul_f32 v[238:239], v[202:203], v[96:97]
	v_pk_mul_f32 v[232:233], v[196:197], v[90:91]
	v_pk_mul_f32 v[234:235], v[198:199], v[92:93]
	v_pk_mul_f32 v[228:229], v[192:193], v[86:87]
	v_pk_mul_f32 v[230:231], v[194:195], v[88:89]
	v_pk_mul_f32 v[224:225], v[188:189], v[82:83]
	v_pk_mul_f32 v[226:227], v[190:191], v[84:85]
	v_cvt_pk_bf16_f32 v66, v236, v237
	v_cvt_pk_bf16_f32 v67, v238, v239
	v_cvt_pk_bf16_f32 v68, v232, v233
	v_cvt_pk_bf16_f32 v69, v234, v235
	v_cvt_pk_bf16_f32 v70, v228, v229
	v_cvt_pk_bf16_f32 v71, v230, v231
	v_cvt_pk_bf16_f32 v72, v224, v225
	v_cvt_pk_bf16_f32 v73, v226, v227
	ds_write_b128 v153, v[66:69]
	ds_write_b128 v153, v[70:73] offset:64
	ds_read_b128 v[208:211], v162
	ds_read_b128 v[146:149], v162 offset:1024
	s_add_u32 s4, s40, 0x4000
	s_addc_u32 s5, s41, 0
	s_waitcnt lgkmcnt(1)
	global_store_dwordx4 v255, v[208:211], s[40:41]
	s_waitcnt lgkmcnt(0)
	global_store_dwordx4 v255, v[146:149], s[4:5]
	s_add_u32 s38, s38, 0x28000
	s_addc_u32 s39, s39, 0
	s_add_u32 s40, s40, 0x28000
	s_addc_u32 s41, s41, 0
	s_waitcnt vmcnt(16)
	v_lshlrev_b32_e32 v236, 16, v248
	v_and_b32_e32 v237, 0xffff0000, v248
	v_lshlrev_b32_e32 v238, 16, v249
	v_and_b32_e32 v239, 0xffff0000, v249
	v_lshlrev_b32_e32 v232, 16, v250
	v_and_b32_e32 v233, 0xffff0000, v250
	v_lshlrev_b32_e32 v234, 16, v251
	v_and_b32_e32 v235, 0xffff0000, v251
	v_lshlrev_b32_e32 v228, 16, v204
	v_and_b32_e32 v229, 0xffff0000, v204
	v_lshlrev_b32_e32 v230, 16, v205
	v_and_b32_e32 v231, 0xffff0000, v205
	v_lshlrev_b32_e32 v224, 16, v206
	v_and_b32_e32 v225, 0xffff0000, v206
	v_lshlrev_b32_e32 v226, 16, v207
	v_and_b32_e32 v227, 0xffff0000, v207
	global_load_dwordx4 v[248:251], v151, s[36:37]
	global_load_dwordx4 v[204:207], v151, s[36:37] offset:64
	v_pk_fma_f32 v[78:79], v[78:79], v[184:185], v[236:237]
	v_pk_fma_f32 v[80:81], v[80:81], v[186:187], v[238:239]
	v_pk_fma_f32 v[74:75], v[74:75], v[180:181], v[232:233]
	v_pk_fma_f32 v[76:77], v[76:77], v[182:183], v[234:235]
	v_pk_fma_f32 v[62:63], v[62:63], v[176:177], v[228:229]
	v_pk_fma_f32 v[64:65], v[64:65], v[178:179], v[230:231]
	v_pk_fma_f32 v[58:59], v[58:59], v[172:173], v[224:225]
	v_pk_fma_f32 v[60:61], v[60:61], v[174:175], v[226:227]
	v_mul_f32_e32 v224, v79, v79
	v_mul_f32_e32 v225, v81, v81
	v_fmac_f32_e32 v224, v78, v78
	v_fmac_f32_e32 v225, v80, v80
	v_add_f32_e32 v224, v224, v225
	v_mul_f32_e32 v225, v75, v75
	v_mul_f32_e32 v226, v77, v77
	v_fmac_f32_e32 v225, v74, v74
	v_fmac_f32_e32 v226, v76, v76
	v_add_f32_e32 v225, v225, v226
	v_add_f32_e32 v224, v224, v225
	v_mul_f32_e32 v225, v63, v63
	v_mul_f32_e32 v226, v65, v65
	v_fmac_f32_e32 v225, v62, v62
	v_fmac_f32_e32 v226, v64, v64
	v_add_f32_e32 v225, v225, v226
	v_mul_f32_e32 v226, v59, v59
	v_mul_f32_e32 v227, v61, v61
	v_fmac_f32_e32 v226, v58, v58
	v_fmac_f32_e32 v227, v60, v60
	v_add_f32_e32 v226, v226, v227
	v_add_f32_e32 v225, v225, v226
	v_add_f32_e32 v223, v224, v225
	v_cvt_pk_bf16_f32 v66, v78, v79
	v_cvt_pk_bf16_f32 v67, v80, v81
	v_cvt_pk_bf16_f32 v68, v74, v75
	v_cvt_pk_bf16_f32 v69, v76, v77
	v_cvt_pk_bf16_f32 v70, v62, v63
	v_cvt_pk_bf16_f32 v71, v64, v65
	v_cvt_pk_bf16_f32 v72, v58, v59
	v_cvt_pk_bf16_f32 v73, v60, v61
	ds_write_b128 v153, v[66:69]
	ds_write_b128 v153, v[70:73] offset:64
	ds_read_b128 v[208:211], v162
	ds_read_b128 v[146:149], v162 offset:1024
	s_add_u32 s4, s38, 0x4000
	s_addc_u32 s5, s39, 0
	s_waitcnt lgkmcnt(1)
	global_store_dwordx4 v255, v[208:211], s[38:39]
	s_waitcnt lgkmcnt(0)
	global_store_dwordx4 v255, v[146:149], s[4:5]
	v_pk_mul_f32 v[236:237], v[200:201], v[78:79]
	v_pk_mul_f32 v[238:239], v[202:203], v[80:81]
	v_pk_mul_f32 v[232:233], v[196:197], v[74:75]
	v_pk_mul_f32 v[234:235], v[198:199], v[76:77]
	v_pk_mul_f32 v[228:229], v[192:193], v[62:63]
	v_pk_mul_f32 v[230:231], v[194:195], v[64:65]
	v_pk_mul_f32 v[224:225], v[188:189], v[58:59]
	v_pk_mul_f32 v[226:227], v[190:191], v[60:61]
	v_cvt_pk_bf16_f32 v66, v236, v237
	v_cvt_pk_bf16_f32 v67, v238, v239
	v_cvt_pk_bf16_f32 v68, v232, v233
	v_cvt_pk_bf16_f32 v69, v234, v235
	v_cvt_pk_bf16_f32 v70, v228, v229
	v_cvt_pk_bf16_f32 v71, v230, v231
	v_cvt_pk_bf16_f32 v72, v224, v225
	v_cvt_pk_bf16_f32 v73, v226, v227
	ds_write_b128 v153, v[66:69]
	ds_write_b128 v153, v[70:73] offset:64
	ds_read_b128 v[208:211], v162
	ds_read_b128 v[146:149], v162 offset:1024
	s_add_u32 s4, s40, 0x4000
	s_addc_u32 s5, s41, 0
	s_waitcnt lgkmcnt(1)
	global_store_dwordx4 v255, v[208:211], s[40:41]
	s_waitcnt lgkmcnt(0)
	global_store_dwordx4 v255, v[146:149], s[4:5]
	s_add_u32 s38, s38, 0x8000
	s_addc_u32 s39, s39, 0
	s_add_u32 s40, s40, 0x8000
	s_addc_u32 s41, s41, 0
	s_waitcnt vmcnt(16)
; #define PG8_LAS __attribute__((address_space(3)))
; __device__ __forceinline__ u32x4 pack8(const f32x4 a, const f32x4 b) { u32x4 w; w.x = cvt_pk_bf16(a[0], a[1]); w.y = cvt_pk_bf16(a[2], a[3]); w.z = cvt_pk_bf16(b[0], b[1]); w.w = cvt_pk_bf16(b[2], b[3]); return w; }
; __device__ __forceinline__ void store_lines(PG8_LAS unsigned char* stg, const u32x4 P0, const u32x4 P1, int fr, int fq, bf16_t* seg0, int pitch) {
;     const int ln = fq * 16 + fr;
; #pragma unroll
;     for (int h = 0; h < 2; ++h) {
;         if ((fr >> 3) == h) { *(PG8_LAS u32x4*)(stg + (fr & 7) * 128 + fq * 16) = P0; *(PG8_LAS u32x4*)(stg + (fr & 7) * 128 + 64 + fq * 16) = P1; }
;         __builtin_amdgcn_wave_barrier(); asm volatile("" ::: "memory");
;         const u32x4 v = *(const PG8_LAS u32x4*)(stg + ln * 16);
;         __builtin_amdgcn_wave_barrier(); asm volatile("" ::: "memory");
;         *(u32x4*)(seg0 + (size_t)(8 * h + (ln >> 3)) * pitch + (ln & 7) * 8) = v; }
;     __device__ __forceinline__ void operator()(const f32x4 (&acc)[2][2][4][2], const Unit& u, int wr, int wc, int fr, int fq) const {
;     ...
;         for (int r = 0; r < 8; ++r) { const int ai = r >> 2, m = r & 3; const int row = EPI_ROW; float sq = 0.f;
;             if (r < 7) RES_LOAD(n16, n32, r + 1);
;             u32x4 pn_[2], ps_[2];
; #pragma unroll
;             for (int bj = 0; bj < 2; ++bj) {
;                 f32x4 o0, o1;
;                 if (XOLD16) unpack8(c16[bj], o0, o1); else { o0 = c32[bj][0]; o1 = c32[bj][1]; }
;                 const f32x4 v0 = o0 + gv[bj][0] * acc[ai][bj][m][0], v1 = o1 + gv[bj][1] * acc[ai][bj][m][1];
;                 pn_[bj] = pack8(v0, v1);
;                 sq += ((v0[0] * v0[0] + v0[1] * v0[1]) + (v0[2] * v0[2] + v0[3] * v0[3])) + ((v1[0] * v1[0] + v1[1] * v1[1]) + (v1[2] * v1[2] + v1[3] * v1[3]));
;                 if (XS) ps_[bj] = pack8(v0 * cs[bj][0], v1 * cs[bj][1]); }
;             { const size_t seg = (size_t)(row - fr) * DM + u.pn * BM + wc * 64;
;               store_lines(st, pn_[0], pn_[1], fr, fq, xnew + seg, DM);
;               if (XS) store_lines(st, ps_[0], ps_[1], fr, fq, xs + seg, DM); }
	v_lshlrev_b32_e32 v236, 16, v50
	v_and_b32_e32 v237, 0xffff0000, v50
	v_lshlrev_b32_e32 v238, 16, v51
	v_and_b32_e32 v239, 0xffff0000, v51
	v_lshlrev_b32_e32 v232, 16, v52
	v_and_b32_e32 v233, 0xffff0000, v52
	v_lshlrev_b32_e32 v234, 16, v53
	v_and_b32_e32 v235, 0xffff0000, v53
	v_lshlrev_b32_e32 v228, 16, v54
	v_and_b32_e32 v229, 0xffff0000, v54
	v_lshlrev_b32_e32 v230, 16, v55
	v_and_b32_e32 v231, 0xffff0000, v55
	v_lshlrev_b32_e32 v224, 16, v56
	v_and_b32_e32 v225, 0xffff0000, v56
	v_lshlrev_b32_e32 v226, 16, v57
	v_and_b32_e32 v227, 0xffff0000, v57
	v_pk_fma_f32 v[46:47], v[46:47], v[184:185], v[236:237]
	v_pk_fma_f32 v[48:49], v[48:49], v[186:187], v[238:239]
	v_pk_fma_f32 v[42:43], v[42:43], v[180:181], v[232:233]
	v_pk_fma_f32 v[44:45], v[44:45], v[182:183], v[234:235]
	v_pk_fma_f32 v[38:39], v[38:39], v[176:177], v[228:229]
	v_pk_fma_f32 v[40:41], v[40:41], v[178:179], v[230:231]
	v_pk_fma_f32 v[34:35], v[34:35], v[172:173], v[224:225]
	v_pk_fma_f32 v[36:37], v[36:37], v[174:175], v[226:227]
	v_mul_f32_e32 v224, v47, v47
	v_mul_f32_e32 v225, v49, v49
	v_fmac_f32_e32 v224, v46, v46
	v_fmac_f32_e32 v225, v48, v48
	v_add_f32_e32 v224, v224, v225
	v_mul_f32_e32 v225, v43, v43
	v_mul_f32_e32 v226, v45, v45
	v_fmac_f32_e32 v225, v42, v42
	v_fmac_f32_e32 v226, v44, v44
	v_add_f32_e32 v225, v225, v226
	v_add_f32_e32 v224, v224, v225
	v_mul_f32_e32 v225, v39, v39
	v_mul_f32_e32 v226, v41, v41
	v_fmac_f32_e32 v225, v38, v38
	v_fmac_f32_e32 v226, v40, v40
	v_add_f32_e32 v225, v225, v226
	v_mul_f32_e32 v226, v35, v35
	v_mul_f32_e32 v227, v37, v37
	v_fmac_f32_e32 v226, v34, v34
	v_fmac_f32_e32 v227, v36, v36
	v_add_f32_e32 v226, v226, v227
	v_add_f32_e32 v225, v225, v226
	v_add_f32_e32 v252, v224, v225
	v_cvt_pk_bf16_f32 v66, v46, v47
	v_cvt_pk_bf16_f32 v67, v48, v49
	v_cvt_pk_bf16_f32 v68, v42, v43
	v_cvt_pk_bf16_f32 v69, v44, v45
	v_cvt_pk_bf16_f32 v70, v38, v39
	v_cvt_pk_bf16_f32 v71, v40, v41
	v_cvt_pk_bf16_f32 v72, v34, v35
	v_cvt_pk_bf16_f32 v73, v36, v37
	ds_write_b128 v153, v[66:69]
	ds_write_b128 v153, v[70:73] offset:64
	ds_read_b128 v[208:211], v162
	ds_read_b128 v[146:149], v162 offset:1024
	s_add_u32 s4, s38, 0x4000
	s_addc_u32 s5, s39, 0
	s_waitcnt lgkmcnt(1)
	global_store_dwordx4 v255, v[208:211], s[38:39]
	s_waitcnt lgkmcnt(0)
	global_store_dwordx4 v255, v[146:149], s[4:5]
	v_pk_mul_f32 v[236:237], v[200:201], v[46:47]
	v_pk_mul_f32 v[238:239], v[202:203], v[48:49]
	v_pk_mul_f32 v[232:233], v[196:197], v[42:43]
	v_pk_mul_f32 v[234:235], v[198:199], v[44:45]
	v_pk_mul_f32 v[228:229], v[192:193], v[38:39]
	v_pk_mul_f32 v[230:231], v[194:195], v[40:41]
	v_pk_mul_f32 v[224:225], v[188:189], v[34:35]
	v_pk_mul_f32 v[226:227], v[190:191], v[36:37]
	v_cvt_pk_bf16_f32 v66, v236, v237
	v_cvt_pk_bf16_f32 v67, v238, v239
	v_cvt_pk_bf16_f32 v68, v232, v233
	v_cvt_pk_bf16_f32 v69, v234, v235
	v_cvt_pk_bf16_f32 v70, v228, v229
	v_cvt_pk_bf16_f32 v71, v230, v231
	v_cvt_pk_bf16_f32 v72, v224, v225
	v_cvt_pk_bf16_f32 v73, v226, v227
	ds_write_b128 v153, v[66:69]
	ds_write_b128 v153, v[70:73] offset:64
	ds_read_b128 v[208:211], v162
	ds_read_b128 v[146:149], v162 offset:1024
	s_add_u32 s4, s40, 0x4000
	s_addc_u32 s5, s41, 0
	s_waitcnt lgkmcnt(1)
	global_store_dwordx4 v255, v[208:211], s[40:41]
	s_waitcnt lgkmcnt(0)
	global_store_dwordx4 v255, v[146:149], s[4:5]
	s_add_u32 s38, s38, 0x8000
	s_addc_u32 s39, s39, 0
	s_add_u32 s40, s40, 0x8000
	s_addc_u32 s41, s41, 0
	s_waitcnt vmcnt(14)
	v_lshlrev_b32_e32 v236, 16, v240
	v_and_b32_e32 v237, 0xffff0000, v240
	v_lshlrev_b32_e32 v238, 16, v241
	v_and_b32_e32 v239, 0xffff0000, v241
	v_lshlrev_b32_e32 v232, 16, v242
	v_and_b32_e32 v233, 0xffff0000, v242
	v_lshlrev_b32_e32 v234, 16, v243
	v_and_b32_e32 v235, 0xffff0000, v243
	v_lshlrev_b32_e32 v228, 16, v244
	v_and_b32_e32 v229, 0xffff0000, v244
	v_lshlrev_b32_e32 v230, 16, v245
	v_and_b32_e32 v231, 0xffff0000, v245
	v_lshlrev_b32_e32 v224, 16, v246
	v_and_b32_e32 v225, 0xffff0000, v246
	v_lshlrev_b32_e32 v226, 16, v247
	v_and_b32_e32 v227, 0xffff0000, v247
	v_pk_fma_f32 v[30:31], v[30:31], v[184:185], v[236:237]
	v_pk_fma_f32 v[32:33], v[32:33], v[186:187], v[238:239]
	v_pk_fma_f32 v[26:27], v[26:27], v[180:181], v[232:233]
	v_pk_fma_f32 v[28:29], v[28:29], v[182:183], v[234:235]
	v_pk_fma_f32 v[22:23], v[22:23], v[176:177], v[228:229]
	v_pk_fma_f32 v[24:25], v[24:25], v[178:179], v[230:231]
	v_pk_fma_f32 v[18:19], v[18:19], v[172:173], v[224:225]
	v_pk_fma_f32 v[20:21], v[20:21], v[174:175], v[226:227]
	v_mul_f32_e32 v224, v31, v31
	v_mul_f32_e32 v225, v33, v33
	v_fmac_f32_e32 v224, v30, v30
	v_fmac_f32_e32 v225, v32, v32
	v_add_f32_e32 v224, v224, v225
	v_mul_f32_e32 v225, v27, v27
	v_mul_f32_e32 v226, v29, v29
	v_fmac_f32_e32 v225, v26, v26
	v_fmac_f32_e32 v226, v28, v28
	v_add_f32_e32 v225, v225, v226
	v_add_f32_e32 v224, v224, v225
	v_mul_f32_e32 v225, v23, v23
	v_mul_f32_e32 v226, v25, v25
	v_fmac_f32_e32 v225, v22, v22
	v_fmac_f32_e32 v226, v24, v24
	v_add_f32_e32 v225, v225, v226
	v_mul_f32_e32 v226, v19, v19
	v_mul_f32_e32 v227, v21, v21
	v_fmac_f32_e32 v226, v18, v18
	v_fmac_f32_e32 v227, v20, v20
	v_add_f32_e32 v226, v226, v227
	v_add_f32_e32 v225, v225, v226
	v_add_f32_e32 v253, v224, v225
	v_cvt_pk_bf16_f32 v66, v30, v31
	v_cvt_pk_bf16_f32 v67, v32, v33
	v_cvt_pk_bf16_f32 v68, v26, v27
	v_cvt_pk_bf16_f32 v69, v28, v29
	v_cvt_pk_bf16_f32 v70, v22, v23
	v_cvt_pk_bf16_f32 v71, v24, v25
	v_cvt_pk_bf16_f32 v72, v18, v19
	v_cvt_pk_bf16_f32 v73, v20, v21
	ds_write_b128 v153, v[66:69]
	ds_write_b128 v153, v[70:73] offset:64
	ds_read_b128 v[208:211], v162
	ds_read_b128 v[146:149], v162 offset:1024
	s_add_u32 s4, s38, 0x4000
	s_addc_u32 s5, s39, 0
	s_waitcnt lgkmcnt(1)
; #define PG8_LAS __attribute__((address_space(3)))
; __device__ __forceinline__ u32x4 pack8(const f32x4 a, const f32x4 b) { u32x4 w; w.x = cvt_pk_bf16(a[0], a[1]); w.y = cvt_pk_bf16(a[2], a[3]); w.z = cvt_pk_bf16(b[0], b[1]); w.w = cvt_pk_bf16(b[2], b[3]); return w; }
; __device__ __forceinline__ void store_lines(PG8_LAS unsigned char* stg, const u32x4 P0, const u32x4 P1, int fr, int fq, bf16_t* seg0, int pitch) {
;     const int ln = fq * 16 + fr;
; #pragma unroll
;     for (int h = 0; h < 2; ++h) {
;         if ((fr >> 3) == h) { *(PG8_LAS u32x4*)(stg + (fr & 7) * 128 + fq * 16) = P0; *(PG8_LAS u32x4*)(stg + (fr & 7) * 128 + 64 + fq * 16) = P1; }
;         __builtin_amdgcn_wave_barrier(); asm volatile("" ::: "memory");
;         const u32x4 v = *(const PG8_LAS u32x4*)(stg + ln * 16);
;         __builtin_amdgcn_wave_barrier(); asm volatile("" ::: "memory");
;         *(u32x4*)(seg0 + (size_t)(8 * h + (ln >> 3)) * pitch + (ln & 7) * 8) = v; }
;     __device__ __forceinline__ void operator()(const f32x4 (&acc)[2][2][4][2], const Unit& u, int wr, int wc, int fr, int fq) const {
;     ...
;             for (int bj = 0; bj < 2; ++bj) {
;                 f32x4 o0, o1;
;                 if (XOLD16) unpack8(c16[bj], o0, o1); else { o0 = c32[bj][0]; o1 = c32[bj][1]; }
;                 const f32x4 v0 = o0 + gv[bj][0] * acc[ai][bj][m][0], v1 = o1 + gv[bj][1] * acc[ai][bj][m][1];
;                 pn_[bj] = pack8(v0, v1);
;                 sq += ((v0[0] * v0[0] + v0[1] * v0[1]) + (v0[2] * v0[2] + v0[3] * v0[3])) + ((v1[0] * v1[0] + v1[1] * v1[1]) + (v1[2] * v1[2] + v1[3] * v1[3]));
;                 if (XS) ps_[bj] = pack8(v0 * cs[bj][0], v1 * cs[bj][1]); }
;             { const size_t seg = (size_t)(row - fr) * DM + u.pn * BM + wc * 64;
;               store_lines(st, pn_[0], pn_[1], fr, fq, xnew + seg, DM);
;               if (XS) store_lines(st, ps_[0], ps_[1], fr, fq, xs + seg, DM); }
;             sq += __shfl_xor(sq, 16); sq += __shfl_xor(sq, 32);
;             if (fq == 0) ssq[(size_t)row * 16 + u.pn * 4 + wc] = sq;
	global_store_dwordx4 v255, v[208:211], s[38:39]
	s_waitcnt lgkmcnt(0)
	global_store_dwordx4 v255, v[146:149], s[4:5]
	v_pk_mul_f32 v[236:237], v[200:201], v[30:31]
	v_pk_mul_f32 v[238:239], v[202:203], v[32:33]
	v_pk_mul_f32 v[232:233], v[196:197], v[26:27]
	v_pk_mul_f32 v[234:235], v[198:199], v[28:29]
	v_pk_mul_f32 v[228:229], v[192:193], v[22:23]
	v_pk_mul_f32 v[230:231], v[194:195], v[24:25]
	v_pk_mul_f32 v[224:225], v[188:189], v[18:19]
	v_pk_mul_f32 v[226:227], v[190:191], v[20:21]
	v_cvt_pk_bf16_f32 v66, v236, v237
	v_cvt_pk_bf16_f32 v67, v238, v239
	v_cvt_pk_bf16_f32 v68, v232, v233
	v_cvt_pk_bf16_f32 v69, v234, v235
	v_cvt_pk_bf16_f32 v70, v228, v229
	v_cvt_pk_bf16_f32 v71, v230, v231
	v_cvt_pk_bf16_f32 v72, v224, v225
	v_cvt_pk_bf16_f32 v73, v226, v227
	ds_write_b128 v153, v[66:69]
	ds_write_b128 v153, v[70:73] offset:64
	ds_read_b128 v[208:211], v162
	ds_read_b128 v[146:149], v162 offset:1024
	s_add_u32 s4, s40, 0x4000
	s_addc_u32 s5, s41, 0
	s_waitcnt lgkmcnt(1)
	global_store_dwordx4 v255, v[208:211], s[40:41]
	s_waitcnt lgkmcnt(0)
	global_store_dwordx4 v255, v[146:149], s[4:5]
	s_add_u32 s38, s38, 0x8000
	s_addc_u32 s39, s39, 0
	s_add_u32 s40, s40, 0x8000
	s_addc_u32 s41, s41, 0
	s_waitcnt vmcnt(12)
	v_lshlrev_b32_e32 v236, 16, v248
	v_and_b32_e32 v237, 0xffff0000, v248
	v_lshlrev_b32_e32 v238, 16, v249
	v_and_b32_e32 v239, 0xffff0000, v249
	v_lshlrev_b32_e32 v232, 16, v250
	v_and_b32_e32 v233, 0xffff0000, v250
	v_lshlrev_b32_e32 v234, 16, v251
	v_and_b32_e32 v235, 0xffff0000, v251
	v_lshlrev_b32_e32 v228, 16, v204
	v_and_b32_e32 v229, 0xffff0000, v204
	v_lshlrev_b32_e32 v230, 16, v205
	v_and_b32_e32 v231, 0xffff0000, v205
	v_lshlrev_b32_e32 v224, 16, v206
	v_and_b32_e32 v225, 0xffff0000, v206
	v_lshlrev_b32_e32 v226, 16, v207
	v_and_b32_e32 v227, 0xffff0000, v207
	v_pk_fma_f32 v[14:15], v[14:15], v[184:185], v[236:237]
	v_pk_fma_f32 v[16:17], v[16:17], v[186:187], v[238:239]
	v_pk_fma_f32 v[10:11], v[10:11], v[180:181], v[232:233]
	v_pk_fma_f32 v[12:13], v[12:13], v[182:183], v[234:235]
	v_pk_fma_f32 v[6:7], v[6:7], v[176:177], v[228:229]
	v_pk_fma_f32 v[8:9], v[8:9], v[178:179], v[230:231]
	v_pk_fma_f32 v[2:3], v[2:3], v[172:173], v[224:225]
	v_pk_fma_f32 v[4:5], v[4:5], v[174:175], v[226:227]
	v_mul_f32_e32 v224, v15, v15
	v_mul_f32_e32 v225, v17, v17
	v_fmac_f32_e32 v224, v14, v14
	v_fmac_f32_e32 v225, v16, v16
	v_add_f32_e32 v224, v224, v225
	v_mul_f32_e32 v225, v11, v11
	v_mul_f32_e32 v226, v13, v13
	v_fmac_f32_e32 v225, v10, v10
	v_fmac_f32_e32 v226, v12, v12
	v_add_f32_e32 v225, v225, v226
	v_add_f32_e32 v224, v224, v225
	v_mul_f32_e32 v225, v7, v7
	v_mul_f32_e32 v226, v9, v9
	v_fmac_f32_e32 v225, v6, v6
	v_fmac_f32_e32 v226, v8, v8
	v_add_f32_e32 v225, v225, v226
	v_mul_f32_e32 v226, v3, v3
	v_mul_f32_e32 v227, v5, v5
	v_fmac_f32_e32 v226, v2, v2
	v_fmac_f32_e32 v227, v4, v4
	v_add_f32_e32 v226, v226, v227
	v_add_f32_e32 v225, v225, v226
	v_add_f32_e32 v150, v224, v225
	v_cvt_pk_bf16_f32 v66, v14, v15
	v_cvt_pk_bf16_f32 v67, v16, v17
	v_cvt_pk_bf16_f32 v68, v10, v11
	v_cvt_pk_bf16_f32 v69, v12, v13
	v_cvt_pk_bf16_f32 v70, v6, v7
	v_cvt_pk_bf16_f32 v71, v8, v9
	v_cvt_pk_bf16_f32 v72, v2, v3
	v_cvt_pk_bf16_f32 v73, v4, v5
	ds_write_b128 v153, v[66:69]
	ds_write_b128 v153, v[70:73] offset:64
	ds_read_b128 v[208:211], v162
	ds_read_b128 v[146:149], v162 offset:1024
	s_add_u32 s4, s38, 0x4000
	s_addc_u32 s5, s39, 0
	s_waitcnt lgkmcnt(1)
	global_store_dwordx4 v255, v[208:211], s[38:39]
	s_waitcnt lgkmcnt(0)
	global_store_dwordx4 v255, v[146:149], s[4:5]
	v_pk_mul_f32 v[236:237], v[200:201], v[14:15]
	v_pk_mul_f32 v[238:239], v[202:203], v[16:17]
	v_pk_mul_f32 v[232:233], v[196:197], v[10:11]
	v_pk_mul_f32 v[234:235], v[198:199], v[12:13]
	v_pk_mul_f32 v[228:229], v[192:193], v[6:7]
	v_pk_mul_f32 v[230:231], v[194:195], v[8:9]
	v_pk_mul_f32 v[224:225], v[188:189], v[2:3]
	v_pk_mul_f32 v[226:227], v[190:191], v[4:5]
	v_cvt_pk_bf16_f32 v66, v236, v237
	v_cvt_pk_bf16_f32 v67, v238, v239
	v_cvt_pk_bf16_f32 v68, v232, v233
	v_cvt_pk_bf16_f32 v69, v234, v235
	v_cvt_pk_bf16_f32 v70, v228, v229
	v_cvt_pk_bf16_f32 v71, v230, v231
	v_cvt_pk_bf16_f32 v72, v224, v225
	v_cvt_pk_bf16_f32 v73, v226, v227
	ds_write_b128 v153, v[66:69]
	ds_write_b128 v153, v[70:73] offset:64
	ds_read_b128 v[208:211], v162
	ds_read_b128 v[146:149], v162 offset:1024
	s_add_u32 s4, s40, 0x4000
	s_addc_u32 s5, s41, 0
	s_waitcnt lgkmcnt(1)
	global_store_dwordx4 v255, v[208:211], s[40:41]
	s_waitcnt lgkmcnt(0)
	global_store_dwordx4 v255, v[146:149], s[4:5]
	v_xor_b32_e32 v208, 16, v217
	v_xor_b32_e32 v209, 32, v217
	v_lshlrev_b32_e32 v208, 2, v208
	v_lshlrev_b32_e32 v209, 2, v209
	ds_bpermute_b32 v66, v208, v218
	ds_bpermute_b32 v67, v208, v219
	ds_bpermute_b32 v68, v208, v221
	ds_bpermute_b32 v69, v208, v222
	ds_bpermute_b32 v70, v208, v223
	ds_bpermute_b32 v71, v208, v252
	ds_bpermute_b32 v72, v208, v253
	ds_bpermute_b32 v73, v208, v150
	s_waitcnt lgkmcnt(0)
	v_add_f32_e32 v218, v218, v66
	v_add_f32_e32 v219, v219, v67
	v_add_f32_e32 v221, v221, v68
	v_add_f32_e32 v222, v222, v69
	v_add_f32_e32 v223, v223, v70
	v_add_f32_e32 v252, v252, v71
	v_add_f32_e32 v253, v253, v72
	v_add_f32_e32 v150, v150, v73
	ds_bpermute_b32 v66, v209, v218
	ds_bpermute_b32 v67, v209, v219
	ds_bpermute_b32 v68, v209, v221
	ds_bpermute_b32 v69, v209, v222
	ds_bpermute_b32 v70, v209, v223
	ds_bpermute_b32 v71, v209, v252
	ds_bpermute_b32 v72, v209, v253
	ds_bpermute_b32 v73, v209, v150
	s_waitcnt lgkmcnt(0)
	v_add_f32_e32 v218, v218, v66
	v_add_f32_e32 v219, v219, v67
	v_add_f32_e32 v221, v221, v68
	v_add_f32_e32 v222, v222, v69
	v_add_f32_e32 v223, v223, v70
	v_add_f32_e32 v252, v252, v71
	v_add_f32_e32 v253, v253, v72
	v_add_f32_e32 v150, v150, v73
	s_lshl_b32 s4, s98, 8
	s_add_i32 s4, s4, s62
	s_lshl_b32 s4, s4, 6
	s_lshl_b32 s5, s14, 4
	s_add_u32 s4, s4, s5
	s_lshl_b32 s5, s61, 2
	s_add_u32 s4, s4, s5
	s_add_u32 s36, s18, s4
	s_addc_u32 s37, s19, 0
	s_add_u32 s38, s36, 0x2000
	s_addc_u32 s39, s37, 0
	s_mov_b64 exec, 0xffff
	global_store_dword v152, v218, s[36:37] offset:0
	global_store_dword v152, v219, s[36:37] offset:1024
	global_store_dword v152, v221, s[36:37] offset:2048
	global_store_dword v152, v222, s[36:37] offset:3072
	global_store_dword v152, v223, s[38:39] offset:0
	global_store_dword v152, v252, s[38:39] offset:1024
	global_store_dword v152, v253, s[38:39] offset:2048
	global_store_dword v152, v150, s[38:39] offset:3072
	s_mov_b64 exec, -1
	s_andn2_b64 vcc, exec, s[2:3]
	s_mov_b64 s[0:1], -1
	s_cbranch_vccnz .LBB0_830
	s_andn2_b64 vcc, exec, s[16:17]
	s_cbranch_vccnz .LBB0_829
	s_barrier
	s_branch .LBB0_829
